# lambda-table inputs loaded at the start of step 0 (before the weight conversions) so the one workgroup that builds the table does not wait on HBM at the end of the step
# baseline (speedup 1.0000x reference)
; #define TIDX tid_opaque()
;     if (ld == 0) ld = K;
;     const int tid = TIDX, lane = tid & 63, w = tid >> 6;
;     const int nkt = K / 64, ntile = (R / 64) * nkt;
;     const int first = ((int)blockIdx.x + rot) % (int)gridDim.x;
;     for (int t_ = first; t_ < ntile * ((REP & 1) + 1); t_ += gridDim.x) { const int t = t_ % ntile;
;         const int r0 = (t / nkt) * 64, k0 = (t % nkt) * 64;
; __device__ void convert_phase(unsigned char* smem, const Params& p, int l) {
;     float* tile = (float*)smem; bf16_t* wt = (bf16_t*)(((unsigned char*)ldp(38)) + OFF_WT);
;     const size_t uo = (size_t)l * DM * DFF;
;     { const float* wg = ((const float*)ldp(2)) + uo; const float* wu = ((const float*)ldp(3)) + uo; const float* gn = ((const float*)ldp(1)) + l * DM;
;       conv_tiles(tile, wt + W_UP1, 5632, 1024, 0, [=](int k, int r) { const int col = (r >> 5) * 16 + (r & 15); return gn[k] * (((r >> 4) & 1) ? wu[(size_t)k * DFF + col] : wg[(size_t)k * DFF + col]); }); }
.LBB0_304:
	s_cmp_eq_u32 s27, 0
	s_cbranch_scc0 .LBB0_407
	s_add_i32 s98, 0, 0x23ec8
	v_mov_b32_e32 v178, s98
	ds_read_b64 v[178:179], v178
	v_readlane_b32 s98, v255, 52
	v_readlane_b32 s99, v255, 53
	s_lshl_b64 s[98:99], s[98:99], 12
	v_lshlrev_b32_e32 v180, 2, v234
	v_mov_b32_e32 v181, 0
	s_waitcnt lgkmcnt(0)
	v_lshl_add_u64 v[178:179], v[178:179], 0, s[98:99]
	v_lshl_add_u64 v[180:181], v[178:179], 0, v[180:181]
	global_load_dword v178, v[180:181], off
	global_load_dword v179, v[180:181], off offset:2048
	s_cmp_lg_u32 s40, -1
	s_cselect_b32 s0, s40, 0
	s_cselect_b32 s1, s41, 0
	s_waitcnt vmcnt(3)
	v_mov_b32_e32 v0, s0
	s_and_b32 s12, s30, 0xffff
	s_add_i32 s0, 0, 0x23e10
	s_cmp_lg_u32 s0, -1
	v_mov_b32_e32 v1, s1
	s_cselect_b32 s0, s0, 0
	ds_read_b64 v[2:3], v0
	s_waitcnt vmcnt(0) lgkmcnt(0)
	s_cselect_b32 s1, s41, 0
	v_mov_b32_e32 v0, s0
	s_add_i32 s0, 0, 0x23e18
	s_cmp_lg_u32 s0, -1
	v_mov_b32_e32 v1, s1
	s_cselect_b32 s0, s0, 0
	ds_read_b64 v[4:5], v0
	s_waitcnt vmcnt(0) lgkmcnt(0)
	s_cselect_b32 s1, s41, 0
	v_mov_b32_e32 v0, s0
	s_add_i32 s0, 0, 0x23e08
	s_cmp_lg_u32 s0, -1
	v_mov_b32_e32 v1, s1
	s_cselect_b32 s0, s0, 0
	s_cselect_b32 s1, s41, 0
	ds_read_b64 v[6:7], v0
	s_waitcnt vmcnt(0) lgkmcnt(0)
	v_mov_b32_e32 v0, s0
	v_mov_b32_e32 v1, s1
	ds_read_b64 v[8:9], v0
	s_waitcnt vmcnt(0) lgkmcnt(0)
	v_readlane_b32 s0, v254, 19
	v_mov_b32_e32 v0, v234
	v_readlane_b32 s1, v254, 20
	s_load_dword s5, s[0:1], 0x0
	v_readlane_b32 s1, v255, 17
	s_lshl_b32 s10, s30, 10
	s_mul_i32 s15, s12, 0x2c0000
	s_waitcnt lgkmcnt(0)
	s_abs_i32 s13, s5
	v_cvt_f32_u32_e32 v1, s13
	s_sub_i32 s0, 0, s13
	v_rcp_iflag_f32_e32 v1, v1
	s_nop 0
	v_mul_f32_e32 v1, 0x4f7ffffe, v1
	v_cvt_u32_f32_e32 v1, v1
	v_readfirstlane_b32 s9, v5
	v_readfirstlane_b32 s14, v1
	s_mul_i32 s0, s0, s14
	s_mul_hi_u32 s0, s14, s0
	s_add_i32 s14, s14, s0
	s_mul_hi_u32 s0, s1, s14
	s_mul_i32 s0, s0, s13
	s_sub_i32 s0, s1, s0
	s_sub_i32 s1, s0, s13
	s_cmp_ge_u32 s0, s13
	s_cselect_b32 s0, s1, s0
	s_sub_i32 s1, s0, s13
	s_cmp_ge_u32 s0, s13
	s_cselect_b32 s0, s1, s0
	s_xor_b32 s0, s0, s3
	s_sub_i32 s11, s0, s3
	s_cmpk_gt_i32 s11, 0x57f
	v_readfirstlane_b32 s1, v3
	v_readfirstlane_b32 s0, v2
	v_readfirstlane_b32 s8, v4
	v_readfirstlane_b32 s17, v7
	v_readfirstlane_b32 s16, v6
	v_readfirstlane_b32 s7, v9
	v_readfirstlane_b32 s6, v8
	s_cbranch_scc1 .LBB0_308
	v_and_b32_e32 v4, 63, v0
	v_ashrrev_i32_e32 v5, 6, v0
	v_and_b32_e32 v6, 15, v0
	v_and_b32_e32 v0, 16, v0
	s_lshl_b32 s18, s10, 2
	v_mov_b32_e32 v1, s17
	v_mov_b32_e32 v2, s9
	v_cmp_eq_u32_e32 vcc, 0, v0
	s_add_u32 s6, s6, s18
	v_mov_b32_e32 v0, s16
	v_cndmask_b32_e32 v1, v1, v2, vcc
	v_mov_b32_e32 v2, s8
	s_movk_i32 s8, 0x104
	s_addc_u32 s7, s7, 0
	v_cndmask_b32_e32 v0, v0, v2, vcc
	s_lshl_b32 s24, s15, 2
	v_lshl_add_u32 v15, v4, 2, 0
	v_lshlrev_b32_e32 v7, 8, v4
	v_lshlrev_b32_e32 v184, 1, v4
	v_lshlrev_b32_e32 v8, 2, v5
	v_mul_lo_u32 v16, v5, s8
	v_lshl_add_u64 v[0:1], v[0:1], 0, s[24:25]
	v_lshl_add_u64 v[2:3], s[0:1], 0, v[184:185]
	v_add3_u32 v7, v15, v7, v8
	v_add_u32_e32 v8, 8, v5
	v_add_u32_e32 v9, 16, v5
	v_add_u32_e32 v10, 24, v5
	v_add_u32_e32 v11, 32, v5
	v_add_u32_e32 v12, 40, v5
	v_add_u32_e32 v13, 48, v5
	v_add_u32_e32 v14, 56, v5
	v_add_u32_e32 v15, v15, v16

; #define TIDX tid_opaque()
; __device__ void convert_phase(unsigned char* smem, const Params& p, int l) {
;     ...
;     if (blockIdx.x == 2 % gridDim.x) { const float* lam = ((const float*)ldp(25)) + l * 1024; for (int i = TIDX; i < 1024; i += 512) sm[4224 + i] = -8.0f * log1pf(expf(-lam[i])); }
.LBB0_370:
	s_mov_b32 s10, 0xbfb8aa3b
	v_add_u32_e32 v4, 0x200, v4
	s_mov_b32 s11, 0x42ce8ed0
	v_cmp_lt_i32_e32 vcc, s16, v4
	s_mov_b32 s12, 0xc2b17218
	s_or_b64 s[8:9], vcc, s[8:9]
	s_mov_b32 s13, 0x3f2aaaab
	v_mov_b32_e32 v14, 0x3ecc95a3
	v_lshl_add_u64 v[2:3], v[2:3], 0, s[14:15]
	s_mov_b32 s14, 0x3f317218
	s_mov_b32 s15, 0x33800000
	s_waitcnt vmcnt(8)
	v_mov_b32_e32 v5, v178
	v_mov_b32_e32 v178, v179
	v_mul_f32_e32 v6, 0xbfb8aa3b, v5
	v_rndne_f32_e32 v7, v6
	v_fma_f32 v8, v5, s10, -v6
	v_sub_f32_e32 v6, v6, v7
	v_fmac_f32_e32 v8, 0xb2a5705f, v5
	v_add_f32_e32 v6, v6, v8
	v_cvt_i32_f32_e32 v7, v7
	v_exp_f32_e32 v6, v6
	v_cmp_nlt_f32_e32 vcc, s11, v5
	v_ldexp_f32 v6, v6, v7
	s_nop 0
	v_cndmask_b32_e32 v6, 0, v6, vcc
	v_cmp_ngt_f32_e32 vcc, s12, v5
	s_nop 1
	v_cndmask_b32_e32 v5, v242, v6, vcc
	v_add_f32_e32 v8, 1.0, v5
	v_add_f32_e32 v9, -1.0, v8
	v_frexp_mant_f32_e32 v10, v8
	v_cvt_f64_f32_e32 v[6:7], v8
	v_sub_f32_e32 v11, v9, v8
	v_frexp_exp_i32_f64_e32 v6, v[6:7]
	v_cmp_gt_f32_e32 vcc, s13, v10
	v_sub_f32_e32 v9, v5, v9
	v_add_f32_e32 v7, 1.0, v11
	v_subbrev_co_u32_e32 v6, vcc, 0, v6, vcc
	v_add_f32_e32 v7, v9, v7
	v_sub_u32_e32 v9, 0, v6
	v_ldexp_f32 v8, v8, v9
	v_add_f32_e32 v10, -1.0, v8
	v_add_f32_e32 v11, 1.0, v8
	v_ldexp_f32 v7, v7, v9
	v_add_f32_e32 v9, 1.0, v10
	v_add_f32_e32 v12, -1.0, v11
	v_sub_f32_e32 v9, v8, v9
	v_sub_f32_e32 v8, v8, v12
	v_add_f32_e32 v12, v7, v9
	v_add_f32_e32 v7, v7, v8
	v_add_f32_e32 v15, v11, v7
	v_rcp_f32_e32 v16, v15
	v_add_f32_e32 v9, v10, v12
	v_sub_f32_e32 v10, v10, v9
	v_sub_f32_e32 v8, v11, v15
	v_mul_f32_e32 v18, v9, v16
	v_add_f32_e32 v17, v12, v10
	v_mul_f32_e32 v10, v15, v18
	v_add_f32_e32 v7, v7, v8
	v_fma_f32 v12, v18, v15, -v10
	v_fmac_f32_e32 v12, v18, v7
	v_add_f32_e32 v8, v10, v12
	v_sub_f32_e32 v11, v9, v8
	v_mov_b32_e32 v13, v8
	v_pk_add_f32 v[8:9], v[8:9], v[10:11] neg_lo:[0,1] neg_hi:[0,1]
	v_cvt_f32_i32_e32 v6, v6
	v_pk_add_f32 v[8:9], v[8:9], v[12:13] neg_lo:[0,1] neg_hi:[0,1]
	v_cmp_neq_f32_e32 vcc, s22, v5
	v_add_f32_e32 v9, v17, v9
	v_add_f32_e32 v8, v8, v9
	v_add_f32_e32 v9, v11, v8
	v_mul_f32_e32 v13, v16, v9
	v_mul_f32_e32 v10, v15, v13
	v_sub_f32_e32 v11, v11, v9
	v_add_f32_e32 v19, v18, v13
	v_fma_f32 v12, v13, v15, -v10
	v_add_f32_e32 v17, v8, v11
	v_sub_f32_e32 v8, v19, v18
	v_fmac_f32_e32 v12, v13, v7
	v_sub_f32_e32 v7, v13, v8
	v_add_f32_e32 v8, v10, v12
	v_sub_f32_e32 v11, v9, v8
	v_mov_b32_e32 v13, v8
	v_pk_add_f32 v[8:9], v[8:9], v[10:11] neg_lo:[0,1] neg_hi:[0,1]
	s_nop 0
	v_pk_add_f32 v[8:9], v[8:9], v[12:13] neg_lo:[0,1] neg_hi:[0,1]
	s_nop 0
	v_add_f32_e32 v9, v17, v9
	v_add_f32_e32 v8, v8, v9
	v_add_f32_e32 v8, v11, v8
	v_mul_f32_e32 v8, v16, v8
	v_add_f32_e32 v7, v7, v8
	v_add_f32_e32 v8, v19, v7
	v_mul_f32_e32 v10, v8, v8
	v_sub_f32_e32 v11, v8, v19
	v_fmamk_f32 v12, v10, 0x3e9b6dac, v14
	v_sub_f32_e32 v11, v7, v11
	v_mul_f32_e32 v7, v8, v10
	v_fmaak_f32 v187, v10, v12, 0x3f2aaada
	v_ldexp_f32 v13, v11, 1
	v_pk_mul_f32 v[10:11], v[6:7], v[186:187]
	v_ldexp_f32 v9, v8, 1
	v_fma_f32 v8, v6, s14, -v10
	v_fmac_f32_e32 v8, 0xb102e308, v6
	v_pk_add_f32 v[6:7], v[10:11], v[8:9]
	v_mov_b32_e32 v12, v10
	v_sub_f32_e32 v16, v7, v9
	v_pk_add_f32 v[14:15], v[6:7], v[10:11] neg_lo:[0,1] neg_hi:[0,1]
	v_sub_f32_e32 v10, v11, v16
	v_add_f32_e32 v13, v13, v10
	v_pk_add_f32 v[10:11], v[6:7], v[12:13]
	v_mov_b32_e32 v9, v6
	v_mov_b32_e32 v15, v11
	v_pk_add_f32 v[18:19], v[8:9], v[14:15] neg_lo:[0,1] neg_hi:[0,1]
	v_pk_add_f32 v[8:9], v[8:9], v[14:15]
	v_mov_b32_e32 v17, v6
	v_pk_add_f32 v[14:15], v[8:9], v[6:7] op_sel:[1,0] op_sel_hi:[0,1] neg_lo:[0,1] neg_hi:[0,1]
	v_mov_b32_e32 v16, v13
	v_mov_b32_e32 v12, v11
	v_mov_b32_e32 v13, v9
	v_pk_mov_b32 v[6:7], v[6:7], v[14:15] op_sel:[1,0]
	v_pk_add_f32 v[10:11], v[10:11], v[14:15] op_sel_hi:[1,0] neg_lo:[0,1] neg_hi:[0,1]
	v_pk_add_f32 v[6:7], v[12:13], v[6:7] neg_lo:[0,1] neg_hi:[0,1]
	v_mov_b32_e32 v10, v18
	v_pk_add_f32 v[6:7], v[16:17], v[6:7] neg_lo:[0,1] neg_hi:[0,1]
	v_mov_b32_e32 v19, v9
	v_pk_add_f32 v[10:11], v[10:11], v[6:7]
	s_nop 0
	v_pk_add_f32 v[12:13], v[10:11], v[10:11] op_sel:[0,1] op_sel_hi:[1,0]
	s_nop 0
	v_pk_add_f32 v[8:9], v[8:9], v[12:13] op_sel:[1,0] op_sel_hi:[0,1]
	v_mov_b32_e32 v11, v8
	v_mov_b32_e32 v7, v12
	v_pk_add_f32 v[12:13], v[10:11], v[18:19] neg_lo:[0,1] neg_hi:[0,1]
	s_nop 0
	v_sub_f32_e32 v9, v10, v12
	v_pk_add_f32 v[6:7], v[6:7], v[12:13] neg_lo:[0,1] neg_hi:[0,1]
	v_sub_f32_e32 v9, v18, v9
	v_add_f32_e32 v6, v6, v9
	v_add_f32_e32 v6, v6, v7
	v_add_f32_e32 v6, v8, v6
	v_cndmask_b32_e32 v6, v242, v6, vcc
	v_cmp_lt_f32_e64 vcc, |v5|, s15
	s_mov_b64 s[14:15], 0x800
	s_nop 0
	v_cndmask_b32_e32 v5, v6, v5, vcc
	v_mul_f32_e32 v5, 0xc1000000, v5
	global_store_dword v[0:1], v5, off
	v_lshl_add_u64 v[0:1], v[0:1], 0, s[14:15]
	s_andn2_b64 exec, exec, s[8:9]
	s_cbranch_execnz .LBB0_370
